# in-proj column tile 14 (beta/g): waves 0 and 4 stream their activation rows and the 32 weight rows directly from global memory in MFMA fragment layout, 3 K-steps in flight; then a load-only copy of th
# baseline (speedup 1.0000x reference)
.Lz255:
	s_and_b32 s100, s33, 0xc0
	s_cbranch_scc1 .Lzc_skip
	v_mbcnt_lo_u32_b32 v110, -1, 0
	v_mbcnt_hi_u32_b32 v110, -1, v110
	v_and_b32_e32 v111, 15, v110
	v_lshrrev_b32_e32 v116, 4, v110
	v_lshlrev_b32_e32 v116, 4, v116
	s_lshr_b32 s100, s33, 8
	s_lshl_b32 s100, s100, 17
	v_lshl_add_u32 v117, v111, 11, v116
	v_add_u32_e32 v117, s100, v117
	v_mov_b32_e32 v92, v117
	v_add_u32_e32 v93, 0x8000, v117
	v_add_u32_e32 v94, 0x10000, v117
	v_add_u32_e32 v95, 0x18000, v117
	v_add_u32_e32 v100, 0x40000, v117
	v_add_u32_e32 v101, 0x48000, v117
	v_add_u32_e32 v102, 0x50000, v117
	v_add_u32_e32 v103, 0x58000, v117
	v_lshrrev_b32_e32 v118, 2, v111
	v_and_b32_e32 v119, 3, v111
	v_lshl_add_u32 v118, v118, 3, v119
	v_lshl_add_u32 v108, v118, 11, v116
	v_add_u32_e32 v109, 0x2000, v108
	global_load_dwordx4 v[128:131], v108, s[8:9] offset:0
	global_load_dwordx4 v[132:135], v109, s[8:9] offset:0
	global_load_dwordx4 v[136:139], v92, s[38:39] offset:0
	global_load_dwordx4 v[140:143], v93, s[38:39] offset:0
	global_load_dwordx4 v[144:147], v94, s[38:39] offset:0
	global_load_dwordx4 v[148:151], v95, s[38:39] offset:0
	global_load_dwordx4 v[164:167], v100, s[38:39] offset:0
	global_load_dwordx4 v[168:171], v101, s[38:39] offset:0
	global_load_dwordx4 v[172:175], v102, s[38:39] offset:0
	global_load_dwordx4 v[176:179], v103, s[38:39] offset:0
	global_load_dwordx4 v[188:191], v108, s[8:9] offset:64
	global_load_dwordx4 v[202:205], v109, s[8:9] offset:64
	global_load_dwordx4 v[206:209], v92, s[38:39] offset:64
	global_load_dwordx4 v[210:213], v93, s[38:39] offset:64
	global_load_dwordx4 v[214:217], v94, s[38:39] offset:64
	global_load_dwordx4 v[218:221], v95, s[38:39] offset:64
	global_load_dwordx4 v[222:225], v100, s[38:39] offset:64
	global_load_dwordx4 v[226:229], v101, s[38:39] offset:64
	global_load_dwordx4 v[0:3], v102, s[38:39] offset:64
	global_load_dwordx4 v[4:7], v103, s[38:39] offset:64
	global_load_dwordx4 v[12:15], v108, s[8:9] offset:128
	global_load_dwordx4 v[20:23], v109, s[8:9] offset:128
	global_load_dwordx4 v[28:31], v92, s[38:39] offset:128
	global_load_dwordx4 v[36:39], v93, s[38:39] offset:128
	global_load_dwordx4 v[44:47], v94, s[38:39] offset:128
	global_load_dwordx4 v[52:55], v95, s[38:39] offset:128
	global_load_dwordx4 v[64:67], v100, s[38:39] offset:128
	global_load_dwordx4 v[68:71], v101, s[38:39] offset:128
	global_load_dwordx4 v[76:79], v102, s[38:39] offset:128
	global_load_dwordx4 v[84:87], v103, s[38:39] offset:128
	s_waitcnt vmcnt(20)
	v_mfma_f32_16x16x32_bf16 v[124:127], v[128:131], v[136:139], 0
	v_mfma_f32_16x16x32_bf16 v[120:123], v[132:135], v[136:139], 0
	v_mfma_f32_16x16x32_bf16 v[112:115], v[128:131], v[140:143], 0
	v_mfma_f32_16x16x32_bf16 v[104:107], v[132:135], v[140:143], 0
	v_mfma_f32_16x16x32_bf16 v[96:99], v[128:131], v[144:147], 0
	v_mfma_f32_16x16x32_bf16 v[88:91], v[132:135], v[144:147], 0
	v_mfma_f32_16x16x32_bf16 v[80:83], v[128:131], v[148:151], 0
	v_mfma_f32_16x16x32_bf16 v[72:75], v[132:135], v[148:151], 0
	v_mfma_f32_16x16x32_bf16 v[60:63], v[128:131], v[164:167], 0
	v_mfma_f32_16x16x32_bf16 v[56:59], v[132:135], v[164:167], 0
	v_mfma_f32_16x16x32_bf16 v[48:51], v[128:131], v[168:171], 0
	v_mfma_f32_16x16x32_bf16 v[40:43], v[132:135], v[168:171], 0
	v_mfma_f32_16x16x32_bf16 v[32:35], v[128:131], v[172:175], 0
	v_mfma_f32_16x16x32_bf16 v[24:27], v[132:135], v[172:175], 0
	v_mfma_f32_16x16x32_bf16 v[16:19], v[128:131], v[176:179], 0
	v_mfma_f32_16x16x32_bf16 v[8:11], v[132:135], v[176:179], 0
	global_load_dwordx4 v[128:131], v108, s[8:9] offset:192
	global_load_dwordx4 v[132:135], v109, s[8:9] offset:192
	global_load_dwordx4 v[136:139], v92, s[38:39] offset:192
	global_load_dwordx4 v[140:143], v93, s[38:39] offset:192
	global_load_dwordx4 v[144:147], v94, s[38:39] offset:192
	global_load_dwordx4 v[148:151], v95, s[38:39] offset:192
	global_load_dwordx4 v[164:167], v100, s[38:39] offset:192
	global_load_dwordx4 v[168:171], v101, s[38:39] offset:192
	global_load_dwordx4 v[172:175], v102, s[38:39] offset:192
	global_load_dwordx4 v[176:179], v103, s[38:39] offset:192
	s_waitcnt vmcnt(20)
	v_mfma_f32_16x16x32_bf16 v[124:127], v[188:191], v[206:209], v[124:127]
	v_mfma_f32_16x16x32_bf16 v[120:123], v[202:205], v[206:209], v[120:123]
	v_mfma_f32_16x16x32_bf16 v[112:115], v[188:191], v[210:213], v[112:115]
	v_mfma_f32_16x16x32_bf16 v[104:107], v[202:205], v[210:213], v[104:107]
	v_mfma_f32_16x16x32_bf16 v[96:99], v[188:191], v[214:217], v[96:99]
	v_mfma_f32_16x16x32_bf16 v[88:91], v[202:205], v[214:217], v[88:91]
	v_mfma_f32_16x16x32_bf16 v[80:83], v[188:191], v[218:221], v[80:83]
	v_mfma_f32_16x16x32_bf16 v[72:75], v[202:205], v[218:221], v[72:75]
	v_mfma_f32_16x16x32_bf16 v[60:63], v[188:191], v[222:225], v[60:63]
	v_mfma_f32_16x16x32_bf16 v[56:59], v[202:205], v[222:225], v[56:59]
	v_mfma_f32_16x16x32_bf16 v[48:51], v[188:191], v[226:229], v[48:51]
	v_mfma_f32_16x16x32_bf16 v[40:43], v[202:205], v[226:229], v[40:43]
	v_mfma_f32_16x16x32_bf16 v[32:35], v[188:191], v[0:3], v[32:35]
	v_mfma_f32_16x16x32_bf16 v[24:27], v[202:205], v[0:3], v[24:27]
	v_mfma_f32_16x16x32_bf16 v[16:19], v[188:191], v[4:7], v[16:19]
	v_mfma_f32_16x16x32_bf16 v[8:11], v[202:205], v[4:7], v[8:11]
	global_load_dwordx4 v[188:191], v108, s[8:9] offset:256
	global_load_dwordx4 v[202:205], v109, s[8:9] offset:256
	global_load_dwordx4 v[206:209], v92, s[38:39] offset:256
	global_load_dwordx4 v[210:213], v93, s[38:39] offset:256
	global_load_dwordx4 v[214:217], v94, s[38:39] offset:256
	global_load_dwordx4 v[218:221], v95, s[38:39] offset:256
	global_load_dwordx4 v[222:225], v100, s[38:39] offset:256
	global_load_dwordx4 v[226:229], v101, s[38:39] offset:256
	global_load_dwordx4 v[0:3], v102, s[38:39] offset:256
	global_load_dwordx4 v[4:7], v103, s[38:39] offset:256
	s_waitcnt vmcnt(20)
	v_mfma_f32_16x16x32_bf16 v[124:127], v[12:15], v[28:31], v[124:127]
	v_mfma_f32_16x16x32_bf16 v[120:123], v[20:23], v[28:31], v[120:123]
	v_mfma_f32_16x16x32_bf16 v[112:115], v[12:15], v[36:39], v[112:115]
	v_mfma_f32_16x16x32_bf16 v[104:107], v[20:23], v[36:39], v[104:107]
	v_mfma_f32_16x16x32_bf16 v[96:99], v[12:15], v[44:47], v[96:99]
	v_mfma_f32_16x16x32_bf16 v[88:91], v[20:23], v[44:47], v[88:91]
	v_mfma_f32_16x16x32_bf16 v[80:83], v[12:15], v[52:55], v[80:83]
	v_mfma_f32_16x16x32_bf16 v[72:75], v[20:23], v[52:55], v[72:75]
	v_mfma_f32_16x16x32_bf16 v[60:63], v[12:15], v[64:67], v[60:63]
	v_mfma_f32_16x16x32_bf16 v[56:59], v[20:23], v[64:67], v[56:59]
	v_mfma_f32_16x16x32_bf16 v[48:51], v[12:15], v[68:71], v[48:51]
	v_mfma_f32_16x16x32_bf16 v[40:43], v[20:23], v[68:71], v[40:43]
	v_mfma_f32_16x16x32_bf16 v[32:35], v[12:15], v[76:79], v[32:35]
	v_mfma_f32_16x16x32_bf16 v[24:27], v[20:23], v[76:79], v[24:27]
	v_mfma_f32_16x16x32_bf16 v[16:19], v[12:15], v[84:87], v[16:19]
	v_mfma_f32_16x16x32_bf16 v[8:11], v[20:23], v[84:87], v[8:11]
	global_load_dwordx4 v[12:15], v108, s[8:9] offset:320
	global_load_dwordx4 v[20:23], v109, s[8:9] offset:320
	global_load_dwordx4 v[28:31], v92, s[38:39] offset:320
	global_load_dwordx4 v[36:39], v93, s[38:39] offset:320
	global_load_dwordx4 v[44:47], v94, s[38:39] offset:320
	global_load_dwordx4 v[52:55], v95, s[38:39] offset:320
	global_load_dwordx4 v[64:67], v100, s[38:39] offset:320
	global_load_dwordx4 v[68:71], v101, s[38:39] offset:320
	global_load_dwordx4 v[76:79], v102, s[38:39] offset:320
	global_load_dwordx4 v[84:87], v103, s[38:39] offset:320
	s_waitcnt vmcnt(20)
	v_mfma_f32_16x16x32_bf16 v[124:127], v[128:131], v[136:139], v[124:127]
	v_mfma_f32_16x16x32_bf16 v[120:123], v[132:135], v[136:139], v[120:123]
	v_mfma_f32_16x16x32_bf16 v[112:115], v[128:131], v[140:143], v[112:115]
	v_mfma_f32_16x16x32_bf16 v[104:107], v[132:135], v[140:143], v[104:107]
	v_mfma_f32_16x16x32_bf16 v[96:99], v[128:131], v[144:147], v[96:99]
	v_mfma_f32_16x16x32_bf16 v[88:91], v[132:135], v[144:147], v[88:91]
	v_mfma_f32_16x16x32_bf16 v[80:83], v[128:131], v[148:151], v[80:83]
	v_mfma_f32_16x16x32_bf16 v[72:75], v[132:135], v[148:151], v[72:75]
	v_mfma_f32_16x16x32_bf16 v[60:63], v[128:131], v[164:167], v[60:63]
	v_mfma_f32_16x16x32_bf16 v[56:59], v[132:135], v[164:167], v[56:59]
	v_mfma_f32_16x16x32_bf16 v[48:51], v[128:131], v[168:171], v[48:51]
	v_mfma_f32_16x16x32_bf16 v[40:43], v[132:135], v[168:171], v[40:43]
	v_mfma_f32_16x16x32_bf16 v[32:35], v[128:131], v[172:175], v[32:35]
	v_mfma_f32_16x16x32_bf16 v[24:27], v[132:135], v[172:175], v[24:27]
	v_mfma_f32_16x16x32_bf16 v[16:19], v[128:131], v[176:179], v[16:19]
	v_mfma_f32_16x16x32_bf16 v[8:11], v[132:135], v[176:179], v[8:11]
	global_load_dwordx4 v[128:131], v108, s[8:9] offset:384
	global_load_dwordx4 v[132:135], v109, s[8:9] offset:384
	global_load_dwordx4 v[136:139], v92, s[38:39] offset:384
	global_load_dwordx4 v[140:143], v93, s[38:39] offset:384
	global_load_dwordx4 v[144:147], v94, s[38:39] offset:384
	global_load_dwordx4 v[148:151], v95, s[38:39] offset:384
	global_load_dwordx4 v[164:167], v100, s[38:39] offset:384
	global_load_dwordx4 v[168:171], v101, s[38:39] offset:384
	global_load_dwordx4 v[172:175], v102, s[38:39] offset:384
	global_load_dwordx4 v[176:179], v103, s[38:39] offset:384
	s_waitcnt vmcnt(20)
	v_mfma_f32_16x16x32_bf16 v[124:127], v[188:191], v[206:209], v[124:127]
	v_mfma_f32_16x16x32_bf16 v[120:123], v[202:205], v[206:209], v[120:123]
	v_mfma_f32_16x16x32_bf16 v[112:115], v[188:191], v[210:213], v[112:115]
	v_mfma_f32_16x16x32_bf16 v[104:107], v[202:205], v[210:213], v[104:107]
	v_mfma_f32_16x16x32_bf16 v[96:99], v[188:191], v[214:217], v[96:99]
	v_mfma_f32_16x16x32_bf16 v[88:91], v[202:205], v[214:217], v[88:91]
	v_mfma_f32_16x16x32_bf16 v[80:83], v[188:191], v[218:221], v[80:83]
	v_mfma_f32_16x16x32_bf16 v[72:75], v[202:205], v[218:221], v[72:75]
	v_mfma_f32_16x16x32_bf16 v[60:63], v[188:191], v[222:225], v[60:63]
	v_mfma_f32_16x16x32_bf16 v[56:59], v[202:205], v[222:225], v[56:59]
	v_mfma_f32_16x16x32_bf16 v[48:51], v[188:191], v[226:229], v[48:51]
	v_mfma_f32_16x16x32_bf16 v[40:43], v[202:205], v[226:229], v[40:43]
	v_mfma_f32_16x16x32_bf16 v[32:35], v[188:191], v[0:3], v[32:35]
	v_mfma_f32_16x16x32_bf16 v[24:27], v[202:205], v[0:3], v[24:27]
	v_mfma_f32_16x16x32_bf16 v[16:19], v[188:191], v[4:7], v[16:19]
	v_mfma_f32_16x16x32_bf16 v[8:11], v[202:205], v[4:7], v[8:11]
	global_load_dwordx4 v[188:191], v108, s[8:9] offset:448
	global_load_dwordx4 v[202:205], v109, s[8:9] offset:448
	global_load_dwordx4 v[206:209], v92, s[38:39] offset:448
	global_load_dwordx4 v[210:213], v93, s[38:39] offset:448
	global_load_dwordx4 v[214:217], v94, s[38:39] offset:448
	global_load_dwordx4 v[218:221], v95, s[38:39] offset:448
	global_load_dwordx4 v[222:225], v100, s[38:39] offset:448
	global_load_dwordx4 v[226:229], v101, s[38:39] offset:448
	global_load_dwordx4 v[0:3], v102, s[38:39] offset:448
	global_load_dwordx4 v[4:7], v103, s[38:39] offset:448
	s_waitcnt vmcnt(20)
	v_mfma_f32_16x16x32_bf16 v[124:127], v[12:15], v[28:31], v[124:127]
	v_mfma_f32_16x16x32_bf16 v[120:123], v[20:23], v[28:31], v[120:123]
	v_mfma_f32_16x16x32_bf16 v[112:115], v[12:15], v[36:39], v[112:115]
	v_mfma_f32_16x16x32_bf16 v[104:107], v[20:23], v[36:39], v[104:107]
	v_mfma_f32_16x16x32_bf16 v[96:99], v[12:15], v[44:47], v[96:99]
	v_mfma_f32_16x16x32_bf16 v[88:91], v[20:23], v[44:47], v[88:91]
	v_mfma_f32_16x16x32_bf16 v[80:83], v[12:15], v[52:55], v[80:83]
	v_mfma_f32_16x16x32_bf16 v[72:75], v[20:23], v[52:55], v[72:75]
	v_mfma_f32_16x16x32_bf16 v[60:63], v[12:15], v[64:67], v[60:63]
	v_mfma_f32_16x16x32_bf16 v[56:59], v[20:23], v[64:67], v[56:59]
	v_mfma_f32_16x16x32_bf16 v[48:51], v[12:15], v[68:71], v[48:51]
	v_mfma_f32_16x16x32_bf16 v[40:43], v[20:23], v[68:71], v[40:43]
	v_mfma_f32_16x16x32_bf16 v[32:35], v[12:15], v[76:79], v[32:35]
	v_mfma_f32_16x16x32_bf16 v[24:27], v[20:23], v[76:79], v[24:27]
	v_mfma_f32_16x16x32_bf16 v[16:19], v[12:15], v[84:87], v[16:19]
	v_mfma_f32_16x16x32_bf16 v[8:11], v[20:23], v[84:87], v[8:11]
	global_load_dwordx4 v[12:15], v108, s[8:9] offset:512
	global_load_dwordx4 v[20:23], v109, s[8:9] offset:512
	global_load_dwordx4 v[28:31], v92, s[38:39] offset:512
	global_load_dwordx4 v[36:39], v93, s[38:39] offset:512
	global_load_dwordx4 v[44:47], v94, s[38:39] offset:512
	global_load_dwordx4 v[52:55], v95, s[38:39] offset:512
	global_load_dwordx4 v[64:67], v100, s[38:39] offset:512
	global_load_dwordx4 v[68:71], v101, s[38:39] offset:512
	global_load_dwordx4 v[76:79], v102, s[38:39] offset:512
	global_load_dwordx4 v[84:87], v103, s[38:39] offset:512
	s_waitcnt vmcnt(20)
	v_mfma_f32_16x16x32_bf16 v[124:127], v[128:131], v[136:139], v[124:127]
	v_mfma_f32_16x16x32_bf16 v[120:123], v[132:135], v[136:139], v[120:123]
	v_mfma_f32_16x16x32_bf16 v[112:115], v[128:131], v[140:143], v[112:115]
	v_mfma_f32_16x16x32_bf16 v[104:107], v[132:135], v[140:143], v[104:107]
	v_mfma_f32_16x16x32_bf16 v[96:99], v[128:131], v[144:147], v[96:99]
	v_mfma_f32_16x16x32_bf16 v[88:91], v[132:135], v[144:147], v[88:91]
	v_mfma_f32_16x16x32_bf16 v[80:83], v[128:131], v[148:151], v[80:83]
	v_mfma_f32_16x16x32_bf16 v[72:75], v[132:135], v[148:151], v[72:75]
	v_mfma_f32_16x16x32_bf16 v[60:63], v[128:131], v[164:167], v[60:63]
	v_mfma_f32_16x16x32_bf16 v[56:59], v[132:135], v[164:167], v[56:59]
	v_mfma_f32_16x16x32_bf16 v[48:51], v[128:131], v[168:171], v[48:51]
	v_mfma_f32_16x16x32_bf16 v[40:43], v[132:135], v[168:171], v[40:43]
	v_mfma_f32_16x16x32_bf16 v[32:35], v[128:131], v[172:175], v[32:35]
	v_mfma_f32_16x16x32_bf16 v[24:27], v[132:135], v[172:175], v[24:27]
	v_mfma_f32_16x16x32_bf16 v[16:19], v[128:131], v[176:179], v[16:19]
	v_mfma_f32_16x16x32_bf16 v[8:11], v[132:135], v[176:179], v[8:11]
	global_load_dwordx4 v[128:131], v108, s[8:9] offset:576
	global_load_dwordx4 v[132:135], v109, s[8:9] offset:576
	global_load_dwordx4 v[136:139], v92, s[38:39] offset:576
	global_load_dwordx4 v[140:143], v93, s[38:39] offset:576
	global_load_dwordx4 v[144:147], v94, s[38:39] offset:576
	global_load_dwordx4 v[148:151], v95, s[38:39] offset:576
	global_load_dwordx4 v[164:167], v100, s[38:39] offset:576
	global_load_dwordx4 v[168:171], v101, s[38:39] offset:576
	global_load_dwordx4 v[172:175], v102, s[38:39] offset:576
	global_load_dwordx4 v[176:179], v103, s[38:39] offset:576
	s_waitcnt vmcnt(20)
	v_mfma_f32_16x16x32_bf16 v[124:127], v[188:191], v[206:209], v[124:127]
	v_mfma_f32_16x16x32_bf16 v[120:123], v[202:205], v[206:209], v[120:123]
	v_mfma_f32_16x16x32_bf16 v[112:115], v[188:191], v[210:213], v[112:115]
	v_mfma_f32_16x16x32_bf16 v[104:107], v[202:205], v[210:213], v[104:107]
	v_mfma_f32_16x16x32_bf16 v[96:99], v[188:191], v[214:217], v[96:99]
	v_mfma_f32_16x16x32_bf16 v[88:91], v[202:205], v[214:217], v[88:91]
	v_mfma_f32_16x16x32_bf16 v[80:83], v[188:191], v[218:221], v[80:83]
	v_mfma_f32_16x16x32_bf16 v[72:75], v[202:205], v[218:221], v[72:75]
	v_mfma_f32_16x16x32_bf16 v[60:63], v[188:191], v[222:225], v[60:63]
	v_mfma_f32_16x16x32_bf16 v[56:59], v[202:205], v[222:225], v[56:59]
	v_mfma_f32_16x16x32_bf16 v[48:51], v[188:191], v[226:229], v[48:51]
	v_mfma_f32_16x16x32_bf16 v[40:43], v[202:205], v[226:229], v[40:43]
	v_mfma_f32_16x16x32_bf16 v[32:35], v[188:191], v[0:3], v[32:35]
	v_mfma_f32_16x16x32_bf16 v[24:27], v[202:205], v[0:3], v[24:27]
	v_mfma_f32_16x16x32_bf16 v[16:19], v[188:191], v[4:7], v[16:19]
	v_mfma_f32_16x16x32_bf16 v[8:11], v[202:205], v[4:7], v[8:11]
	global_load_dwordx4 v[188:191], v108, s[8:9] offset:640
	global_load_dwordx4 v[202:205], v109, s[8:9] offset:640
	global_load_dwordx4 v[206:209], v92, s[38:39] offset:640
	global_load_dwordx4 v[210:213], v93, s[38:39] offset:640
	global_load_dwordx4 v[214:217], v94, s[38:39] offset:640
	global_load_dwordx4 v[218:221], v95, s[38:39] offset:640
	global_load_dwordx4 v[222:225], v100, s[38:39] offset:640
	global_load_dwordx4 v[226:229], v101, s[38:39] offset:640
	global_load_dwordx4 v[0:3], v102, s[38:39] offset:640
	global_load_dwordx4 v[4:7], v103, s[38:39] offset:640
	s_waitcnt vmcnt(20)
	v_mfma_f32_16x16x32_bf16 v[124:127], v[12:15], v[28:31], v[124:127]
	v_mfma_f32_16x16x32_bf16 v[120:123], v[20:23], v[28:31], v[120:123]
	v_mfma_f32_16x16x32_bf16 v[112:115], v[12:15], v[36:39], v[112:115]
	v_mfma_f32_16x16x32_bf16 v[104:107], v[20:23], v[36:39], v[104:107]
	v_mfma_f32_16x16x32_bf16 v[96:99], v[12:15], v[44:47], v[96:99]
	v_mfma_f32_16x16x32_bf16 v[88:91], v[20:23], v[44:47], v[88:91]
	v_mfma_f32_16x16x32_bf16 v[80:83], v[12:15], v[52:55], v[80:83]
	v_mfma_f32_16x16x32_bf16 v[72:75], v[20:23], v[52:55], v[72:75]
	v_mfma_f32_16x16x32_bf16 v[60:63], v[12:15], v[64:67], v[60:63]
	v_mfma_f32_16x16x32_bf16 v[56:59], v[20:23], v[64:67], v[56:59]
	v_mfma_f32_16x16x32_bf16 v[48:51], v[12:15], v[68:71], v[48:51]
	v_mfma_f32_16x16x32_bf16 v[40:43], v[20:23], v[68:71], v[40:43]
	v_mfma_f32_16x16x32_bf16 v[32:35], v[12:15], v[76:79], v[32:35]
	v_mfma_f32_16x16x32_bf16 v[24:27], v[20:23], v[76:79], v[24:27]
	v_mfma_f32_16x16x32_bf16 v[16:19], v[12:15], v[84:87], v[16:19]
	v_mfma_f32_16x16x32_bf16 v[8:11], v[20:23], v[84:87], v[8:11]
	global_load_dwordx4 v[12:15], v108, s[8:9] offset:704
	global_load_dwordx4 v[20:23], v109, s[8:9] offset:704
	global_load_dwordx4 v[28:31], v92, s[38:39] offset:704
	global_load_dwordx4 v[36:39], v93, s[38:39] offset:704
	global_load_dwordx4 v[44:47], v94, s[38:39] offset:704
	global_load_dwordx4 v[52:55], v95, s[38:39] offset:704
	global_load_dwordx4 v[64:67], v100, s[38:39] offset:704
	global_load_dwordx4 v[68:71], v101, s[38:39] offset:704
	global_load_dwordx4 v[76:79], v102, s[38:39] offset:704
	global_load_dwordx4 v[84:87], v103, s[38:39] offset:704
	s_waitcnt vmcnt(20)
	v_mfma_f32_16x16x32_bf16 v[124:127], v[128:131], v[136:139], v[124:127]
	v_mfma_f32_16x16x32_bf16 v[120:123], v[132:135], v[136:139], v[120:123]
	v_mfma_f32_16x16x32_bf16 v[112:115], v[128:131], v[140:143], v[112:115]
	v_mfma_f32_16x16x32_bf16 v[104:107], v[132:135], v[140:143], v[104:107]
	v_mfma_f32_16x16x32_bf16 v[96:99], v[128:131], v[144:147], v[96:99]
	v_mfma_f32_16x16x32_bf16 v[88:91], v[132:135], v[144:147], v[88:91]
	v_mfma_f32_16x16x32_bf16 v[80:83], v[128:131], v[148:151], v[80:83]
	v_mfma_f32_16x16x32_bf16 v[72:75], v[132:135], v[148:151], v[72:75]
	v_mfma_f32_16x16x32_bf16 v[60:63], v[128:131], v[164:167], v[60:63]
	v_mfma_f32_16x16x32_bf16 v[56:59], v[132:135], v[164:167], v[56:59]
	v_mfma_f32_16x16x32_bf16 v[48:51], v[128:131], v[168:171], v[48:51]
	v_mfma_f32_16x16x32_bf16 v[40:43], v[132:135], v[168:171], v[40:43]
	v_mfma_f32_16x16x32_bf16 v[32:35], v[128:131], v[172:175], v[32:35]
	v_mfma_f32_16x16x32_bf16 v[24:27], v[132:135], v[172:175], v[24:27]
	v_mfma_f32_16x16x32_bf16 v[16:19], v[128:131], v[176:179], v[16:19]
	v_mfma_f32_16x16x32_bf16 v[8:11], v[132:135], v[176:179], v[8:11]
	global_load_dwordx4 v[128:131], v108, s[8:9] offset:768
	global_load_dwordx4 v[132:135], v109, s[8:9] offset:768
	global_load_dwordx4 v[136:139], v92, s[38:39] offset:768
	global_load_dwordx4 v[140:143], v93, s[38:39] offset:768
	global_load_dwordx4 v[144:147], v94, s[38:39] offset:768
	global_load_dwordx4 v[148:151], v95, s[38:39] offset:768
	global_load_dwordx4 v[164:167], v100, s[38:39] offset:768
	global_load_dwordx4 v[168:171], v101, s[38:39] offset:768
	global_load_dwordx4 v[172:175], v102, s[38:39] offset:768
	global_load_dwordx4 v[176:179], v103, s[38:39] offset:768
	s_waitcnt vmcnt(20)
	v_mfma_f32_16x16x32_bf16 v[124:127], v[188:191], v[206:209], v[124:127]
	v_mfma_f32_16x16x32_bf16 v[120:123], v[202:205], v[206:209], v[120:123]
	v_mfma_f32_16x16x32_bf16 v[112:115], v[188:191], v[210:213], v[112:115]
	v_mfma_f32_16x16x32_bf16 v[104:107], v[202:205], v[210:213], v[104:107]
	v_mfma_f32_16x16x32_bf16 v[96:99], v[188:191], v[214:217], v[96:99]
	v_mfma_f32_16x16x32_bf16 v[88:91], v[202:205], v[214:217], v[88:91]
	v_mfma_f32_16x16x32_bf16 v[80:83], v[188:191], v[218:221], v[80:83]
	v_mfma_f32_16x16x32_bf16 v[72:75], v[202:205], v[218:221], v[72:75]
	v_mfma_f32_16x16x32_bf16 v[60:63], v[188:191], v[222:225], v[60:63]
	v_mfma_f32_16x16x32_bf16 v[56:59], v[202:205], v[222:225], v[56:59]
	v_mfma_f32_16x16x32_bf16 v[48:51], v[188:191], v[226:229], v[48:51]
	v_mfma_f32_16x16x32_bf16 v[40:43], v[202:205], v[226:229], v[40:43]
	v_mfma_f32_16x16x32_bf16 v[32:35], v[188:191], v[0:3], v[32:35]
	v_mfma_f32_16x16x32_bf16 v[24:27], v[202:205], v[0:3], v[24:27]
	v_mfma_f32_16x16x32_bf16 v[16:19], v[188:191], v[4:7], v[16:19]
	v_mfma_f32_16x16x32_bf16 v[8:11], v[202:205], v[4:7], v[8:11]
	global_load_dwordx4 v[188:191], v108, s[8:9] offset:832
	global_load_dwordx4 v[202:205], v109, s[8:9] offset:832
	global_load_dwordx4 v[206:209], v92, s[38:39] offset:832
	global_load_dwordx4 v[210:213], v93, s[38:39] offset:832
	global_load_dwordx4 v[214:217], v94, s[38:39] offset:832
	global_load_dwordx4 v[218:221], v95, s[38:39] offset:832
	global_load_dwordx4 v[222:225], v100, s[38:39] offset:832
	global_load_dwordx4 v[226:229], v101, s[38:39] offset:832
	global_load_dwordx4 v[0:3], v102, s[38:39] offset:832
	global_load_dwordx4 v[4:7], v103, s[38:39] offset:832
	s_waitcnt vmcnt(20)
	v_mfma_f32_16x16x32_bf16 v[124:127], v[12:15], v[28:31], v[124:127]
	v_mfma_f32_16x16x32_bf16 v[120:123], v[20:23], v[28:31], v[120:123]
	v_mfma_f32_16x16x32_bf16 v[112:115], v[12:15], v[36:39], v[112:115]
	v_mfma_f32_16x16x32_bf16 v[104:107], v[20:23], v[36:39], v[104:107]
	v_mfma_f32_16x16x32_bf16 v[96:99], v[12:15], v[44:47], v[96:99]
	v_mfma_f32_16x16x32_bf16 v[88:91], v[20:23], v[44:47], v[88:91]
	v_mfma_f32_16x16x32_bf16 v[80:83], v[12:15], v[52:55], v[80:83]
	v_mfma_f32_16x16x32_bf16 v[72:75], v[20:23], v[52:55], v[72:75]
	v_mfma_f32_16x16x32_bf16 v[60:63], v[12:15], v[64:67], v[60:63]
	v_mfma_f32_16x16x32_bf16 v[56:59], v[20:23], v[64:67], v[56:59]
	v_mfma_f32_16x16x32_bf16 v[48:51], v[12:15], v[68:71], v[48:51]
	v_mfma_f32_16x16x32_bf16 v[40:43], v[20:23], v[68:71], v[40:43]
	v_mfma_f32_16x16x32_bf16 v[32:35], v[12:15], v[76:79], v[32:35]
	v_mfma_f32_16x16x32_bf16 v[24:27], v[20:23], v[76:79], v[24:27]
	v_mfma_f32_16x16x32_bf16 v[16:19], v[12:15], v[84:87], v[16:19]
	v_mfma_f32_16x16x32_bf16 v[8:11], v[20:23], v[84:87], v[8:11]
	global_load_dwordx4 v[12:15], v108, s[8:9] offset:896
	global_load_dwordx4 v[20:23], v109, s[8:9] offset:896
	global_load_dwordx4 v[28:31], v92, s[38:39] offset:896
	global_load_dwordx4 v[36:39], v93, s[38:39] offset:896
	global_load_dwordx4 v[44:47], v94, s[38:39] offset:896
	global_load_dwordx4 v[52:55], v95, s[38:39] offset:896
	global_load_dwordx4 v[64:67], v100, s[38:39] offset:896
	global_load_dwordx4 v[68:71], v101, s[38:39] offset:896
	global_load_dwordx4 v[76:79], v102, s[38:39] offset:896
	global_load_dwordx4 v[84:87], v103, s[38:39] offset:896
	s_waitcnt vmcnt(20)
	v_mfma_f32_16x16x32_bf16 v[124:127], v[128:131], v[136:139], v[124:127]
	v_mfma_f32_16x16x32_bf16 v[120:123], v[132:135], v[136:139], v[120:123]
	v_mfma_f32_16x16x32_bf16 v[112:115], v[128:131], v[140:143], v[112:115]
	v_mfma_f32_16x16x32_bf16 v[104:107], v[132:135], v[140:143], v[104:107]
	v_mfma_f32_16x16x32_bf16 v[96:99], v[128:131], v[144:147], v[96:99]
	v_mfma_f32_16x16x32_bf16 v[88:91], v[132:135], v[144:147], v[88:91]
	v_mfma_f32_16x16x32_bf16 v[80:83], v[128:131], v[148:151], v[80:83]
	v_mfma_f32_16x16x32_bf16 v[72:75], v[132:135], v[148:151], v[72:75]
	v_mfma_f32_16x16x32_bf16 v[60:63], v[128:131], v[164:167], v[60:63]
	v_mfma_f32_16x16x32_bf16 v[56:59], v[132:135], v[164:167], v[56:59]
	v_mfma_f32_16x16x32_bf16 v[48:51], v[128:131], v[168:171], v[48:51]
	v_mfma_f32_16x16x32_bf16 v[40:43], v[132:135], v[168:171], v[40:43]
	v_mfma_f32_16x16x32_bf16 v[32:35], v[128:131], v[172:175], v[32:35]
	v_mfma_f32_16x16x32_bf16 v[24:27], v[132:135], v[172:175], v[24:27]
	v_mfma_f32_16x16x32_bf16 v[16:19], v[128:131], v[176:179], v[16:19]
	v_mfma_f32_16x16x32_bf16 v[8:11], v[132:135], v[176:179], v[8:11]
	global_load_dwordx4 v[128:131], v108, s[8:9] offset:960
	global_load_dwordx4 v[132:135], v109, s[8:9] offset:960
	global_load_dwordx4 v[136:139], v92, s[38:39] offset:960
	global_load_dwordx4 v[140:143], v93, s[38:39] offset:960
	global_load_dwordx4 v[144:147], v94, s[38:39] offset:960
	global_load_dwordx4 v[148:151], v95, s[38:39] offset:960
	global_load_dwordx4 v[164:167], v100, s[38:39] offset:960
	global_load_dwordx4 v[168:171], v101, s[38:39] offset:960
	global_load_dwordx4 v[172:175], v102, s[38:39] offset:960
	global_load_dwordx4 v[176:179], v103, s[38:39] offset:960
	s_waitcnt vmcnt(20)
	v_mfma_f32_16x16x32_bf16 v[124:127], v[188:191], v[206:209], v[124:127]
	v_mfma_f32_16x16x32_bf16 v[120:123], v[202:205], v[206:209], v[120:123]
	v_mfma_f32_16x16x32_bf16 v[112:115], v[188:191], v[210:213], v[112:115]
	v_mfma_f32_16x16x32_bf16 v[104:107], v[202:205], v[210:213], v[104:107]
	v_mfma_f32_16x16x32_bf16 v[96:99], v[188:191], v[214:217], v[96:99]
	v_mfma_f32_16x16x32_bf16 v[88:91], v[202:205], v[214:217], v[88:91]
	v_mfma_f32_16x16x32_bf16 v[80:83], v[188:191], v[218:221], v[80:83]
	v_mfma_f32_16x16x32_bf16 v[72:75], v[202:205], v[218:221], v[72:75]
	v_mfma_f32_16x16x32_bf16 v[60:63], v[188:191], v[222:225], v[60:63]
	v_mfma_f32_16x16x32_bf16 v[56:59], v[202:205], v[222:225], v[56:59]
	v_mfma_f32_16x16x32_bf16 v[48:51], v[188:191], v[226:229], v[48:51]
	v_mfma_f32_16x16x32_bf16 v[40:43], v[202:205], v[226:229], v[40:43]
	v_mfma_f32_16x16x32_bf16 v[32:35], v[188:191], v[0:3], v[32:35]
	v_mfma_f32_16x16x32_bf16 v[24:27], v[202:205], v[0:3], v[24:27]
	v_mfma_f32_16x16x32_bf16 v[16:19], v[188:191], v[4:7], v[16:19]
	v_mfma_f32_16x16x32_bf16 v[8:11], v[202:205], v[4:7], v[8:11]
	global_load_dwordx4 v[188:191], v108, s[8:9] offset:1024
	global_load_dwordx4 v[202:205], v109, s[8:9] offset:1024
	global_load_dwordx4 v[206:209], v92, s[38:39] offset:1024
	global_load_dwordx4 v[210:213], v93, s[38:39] offset:1024
	global_load_dwordx4 v[214:217], v94, s[38:39] offset:1024
	global_load_dwordx4 v[218:221], v95, s[38:39] offset:1024
	global_load_dwordx4 v[222:225], v100, s[38:39] offset:1024
	global_load_dwordx4 v[226:229], v101, s[38:39] offset:1024
	global_load_dwordx4 v[0:3], v102, s[38:39] offset:1024
	global_load_dwordx4 v[4:7], v103, s[38:39] offset:1024
	s_waitcnt vmcnt(20)
	v_mfma_f32_16x16x32_bf16 v[124:127], v[12:15], v[28:31], v[124:127]
	v_mfma_f32_16x16x32_bf16 v[120:123], v[20:23], v[28:31], v[120:123]
	v_mfma_f32_16x16x32_bf16 v[112:115], v[12:15], v[36:39], v[112:115]
	v_mfma_f32_16x16x32_bf16 v[104:107], v[20:23], v[36:39], v[104:107]
	v_mfma_f32_16x16x32_bf16 v[96:99], v[12:15], v[44:47], v[96:99]
	v_mfma_f32_16x16x32_bf16 v[88:91], v[20:23], v[44:47], v[88:91]
	v_mfma_f32_16x16x32_bf16 v[80:83], v[12:15], v[52:55], v[80:83]
	v_mfma_f32_16x16x32_bf16 v[72:75], v[20:23], v[52:55], v[72:75]
	v_mfma_f32_16x16x32_bf16 v[60:63], v[12:15], v[64:67], v[60:63]
	v_mfma_f32_16x16x32_bf16 v[56:59], v[20:23], v[64:67], v[56:59]
	v_mfma_f32_16x16x32_bf16 v[48:51], v[12:15], v[68:71], v[48:51]
	v_mfma_f32_16x16x32_bf16 v[40:43], v[20:23], v[68:71], v[40:43]
	v_mfma_f32_16x16x32_bf16 v[32:35], v[12:15], v[76:79], v[32:35]
	v_mfma_f32_16x16x32_bf16 v[24:27], v[20:23], v[76:79], v[24:27]
	v_mfma_f32_16x16x32_bf16 v[16:19], v[12:15], v[84:87], v[16:19]
	v_mfma_f32_16x16x32_bf16 v[8:11], v[20:23], v[84:87], v[8:11]
	global_load_dwordx4 v[12:15], v108, s[8:9] offset:1088
	global_load_dwordx4 v[20:23], v109, s[8:9] offset:1088
	global_load_dwordx4 v[28:31], v92, s[38:39] offset:1088
	global_load_dwordx4 v[36:39], v93, s[38:39] offset:1088
	global_load_dwordx4 v[44:47], v94, s[38:39] offset:1088
	global_load_dwordx4 v[52:55], v95, s[38:39] offset:1088
	global_load_dwordx4 v[64:67], v100, s[38:39] offset:1088
	global_load_dwordx4 v[68:71], v101, s[38:39] offset:1088
	global_load_dwordx4 v[76:79], v102, s[38:39] offset:1088
	global_load_dwordx4 v[84:87], v103, s[38:39] offset:1088
	s_waitcnt vmcnt(20)
	v_mfma_f32_16x16x32_bf16 v[124:127], v[128:131], v[136:139], v[124:127]
	v_mfma_f32_16x16x32_bf16 v[120:123], v[132:135], v[136:139], v[120:123]
	v_mfma_f32_16x16x32_bf16 v[112:115], v[128:131], v[140:143], v[112:115]
	v_mfma_f32_16x16x32_bf16 v[104:107], v[132:135], v[140:143], v[104:107]
	v_mfma_f32_16x16x32_bf16 v[96:99], v[128:131], v[144:147], v[96:99]
	v_mfma_f32_16x16x32_bf16 v[88:91], v[132:135], v[144:147], v[88:91]
	v_mfma_f32_16x16x32_bf16 v[80:83], v[128:131], v[148:151], v[80:83]
	v_mfma_f32_16x16x32_bf16 v[72:75], v[132:135], v[148:151], v[72:75]
	v_mfma_f32_16x16x32_bf16 v[60:63], v[128:131], v[164:167], v[60:63]
	v_mfma_f32_16x16x32_bf16 v[56:59], v[132:135], v[164:167], v[56:59]
	v_mfma_f32_16x16x32_bf16 v[48:51], v[128:131], v[168:171], v[48:51]
	v_mfma_f32_16x16x32_bf16 v[40:43], v[132:135], v[168:171], v[40:43]
	v_mfma_f32_16x16x32_bf16 v[32:35], v[128:131], v[172:175], v[32:35]
	v_mfma_f32_16x16x32_bf16 v[24:27], v[132:135], v[172:175], v[24:27]
	v_mfma_f32_16x16x32_bf16 v[16:19], v[128:131], v[176:179], v[16:19]
	v_mfma_f32_16x16x32_bf16 v[8:11], v[132:135], v[176:179], v[8:11]
	global_load_dwordx4 v[128:131], v108, s[8:9] offset:1152
	global_load_dwordx4 v[132:135], v109, s[8:9] offset:1152
	global_load_dwordx4 v[136:139], v92, s[38:39] offset:1152
	global_load_dwordx4 v[140:143], v93, s[38:39] offset:1152
	global_load_dwordx4 v[144:147], v94, s[38:39] offset:1152
	global_load_dwordx4 v[148:151], v95, s[38:39] offset:1152
	global_load_dwordx4 v[164:167], v100, s[38:39] offset:1152
	global_load_dwordx4 v[168:171], v101, s[38:39] offset:1152
	global_load_dwordx4 v[172:175], v102, s[38:39] offset:1152
	global_load_dwordx4 v[176:179], v103, s[38:39] offset:1152
	s_waitcnt vmcnt(20)
	v_mfma_f32_16x16x32_bf16 v[124:127], v[188:191], v[206:209], v[124:127]
	v_mfma_f32_16x16x32_bf16 v[120:123], v[202:205], v[206:209], v[120:123]
	v_mfma_f32_16x16x32_bf16 v[112:115], v[188:191], v[210:213], v[112:115]
	v_mfma_f32_16x16x32_bf16 v[104:107], v[202:205], v[210:213], v[104:107]
	v_mfma_f32_16x16x32_bf16 v[96:99], v[188:191], v[214:217], v[96:99]
	v_mfma_f32_16x16x32_bf16 v[88:91], v[202:205], v[214:217], v[88:91]
	v_mfma_f32_16x16x32_bf16 v[80:83], v[188:191], v[218:221], v[80:83]
	v_mfma_f32_16x16x32_bf16 v[72:75], v[202:205], v[218:221], v[72:75]
	v_mfma_f32_16x16x32_bf16 v[60:63], v[188:191], v[222:225], v[60:63]
	v_mfma_f32_16x16x32_bf16 v[56:59], v[202:205], v[222:225], v[56:59]
	v_mfma_f32_16x16x32_bf16 v[48:51], v[188:191], v[226:229], v[48:51]
	v_mfma_f32_16x16x32_bf16 v[40:43], v[202:205], v[226:229], v[40:43]
	v_mfma_f32_16x16x32_bf16 v[32:35], v[188:191], v[0:3], v[32:35]
	v_mfma_f32_16x16x32_bf16 v[24:27], v[202:205], v[0:3], v[24:27]
	v_mfma_f32_16x16x32_bf16 v[16:19], v[188:191], v[4:7], v[16:19]
	v_mfma_f32_16x16x32_bf16 v[8:11], v[202:205], v[4:7], v[8:11]
	global_load_dwordx4 v[188:191], v108, s[8:9] offset:1216
	global_load_dwordx4 v[202:205], v109, s[8:9] offset:1216
	global_load_dwordx4 v[206:209], v92, s[38:39] offset:1216
	global_load_dwordx4 v[210:213], v93, s[38:39] offset:1216
	global_load_dwordx4 v[214:217], v94, s[38:39] offset:1216
	global_load_dwordx4 v[218:221], v95, s[38:39] offset:1216
	global_load_dwordx4 v[222:225], v100, s[38:39] offset:1216
	global_load_dwordx4 v[226:229], v101, s[38:39] offset:1216
	global_load_dwordx4 v[0:3], v102, s[38:39] offset:1216
	global_load_dwordx4 v[4:7], v103, s[38:39] offset:1216
	s_waitcnt vmcnt(20)
	v_mfma_f32_16x16x32_bf16 v[124:127], v[12:15], v[28:31], v[124:127]
	v_mfma_f32_16x16x32_bf16 v[120:123], v[20:23], v[28:31], v[120:123]
	v_mfma_f32_16x16x32_bf16 v[112:115], v[12:15], v[36:39], v[112:115]
	v_mfma_f32_16x16x32_bf16 v[104:107], v[20:23], v[36:39], v[104:107]
	v_mfma_f32_16x16x32_bf16 v[96:99], v[12:15], v[44:47], v[96:99]
	v_mfma_f32_16x16x32_bf16 v[88:91], v[20:23], v[44:47], v[88:91]
	v_mfma_f32_16x16x32_bf16 v[80:83], v[12:15], v[52:55], v[80:83]
	v_mfma_f32_16x16x32_bf16 v[72:75], v[20:23], v[52:55], v[72:75]
	v_mfma_f32_16x16x32_bf16 v[60:63], v[12:15], v[64:67], v[60:63]
	v_mfma_f32_16x16x32_bf16 v[56:59], v[20:23], v[64:67], v[56:59]
	v_mfma_f32_16x16x32_bf16 v[48:51], v[12:15], v[68:71], v[48:51]
	v_mfma_f32_16x16x32_bf16 v[40:43], v[20:23], v[68:71], v[40:43]
	v_mfma_f32_16x16x32_bf16 v[32:35], v[12:15], v[76:79], v[32:35]
	v_mfma_f32_16x16x32_bf16 v[24:27], v[20:23], v[76:79], v[24:27]
	v_mfma_f32_16x16x32_bf16 v[16:19], v[12:15], v[84:87], v[16:19]
	v_mfma_f32_16x16x32_bf16 v[8:11], v[20:23], v[84:87], v[8:11]
	global_load_dwordx4 v[12:15], v108, s[8:9] offset:1280
	global_load_dwordx4 v[20:23], v109, s[8:9] offset:1280
	global_load_dwordx4 v[28:31], v92, s[38:39] offset:1280
	global_load_dwordx4 v[36:39], v93, s[38:39] offset:1280
	global_load_dwordx4 v[44:47], v94, s[38:39] offset:1280
	global_load_dwordx4 v[52:55], v95, s[38:39] offset:1280
	global_load_dwordx4 v[64:67], v100, s[38:39] offset:1280
	global_load_dwordx4 v[68:71], v101, s[38:39] offset:1280
	global_load_dwordx4 v[76:79], v102, s[38:39] offset:1280
	global_load_dwordx4 v[84:87], v103, s[38:39] offset:1280
	s_waitcnt vmcnt(20)
	v_mfma_f32_16x16x32_bf16 v[124:127], v[128:131], v[136:139], v[124:127]
	v_mfma_f32_16x16x32_bf16 v[120:123], v[132:135], v[136:139], v[120:123]
	v_mfma_f32_16x16x32_bf16 v[112:115], v[128:131], v[140:143], v[112:115]
	v_mfma_f32_16x16x32_bf16 v[104:107], v[132:135], v[140:143], v[104:107]
	v_mfma_f32_16x16x32_bf16 v[96:99], v[128:131], v[144:147], v[96:99]
	v_mfma_f32_16x16x32_bf16 v[88:91], v[132:135], v[144:147], v[88:91]
	v_mfma_f32_16x16x32_bf16 v[80:83], v[128:131], v[148:151], v[80:83]
	v_mfma_f32_16x16x32_bf16 v[72:75], v[132:135], v[148:151], v[72:75]
	v_mfma_f32_16x16x32_bf16 v[60:63], v[128:131], v[164:167], v[60:63]
	v_mfma_f32_16x16x32_bf16 v[56:59], v[132:135], v[164:167], v[56:59]
	v_mfma_f32_16x16x32_bf16 v[48:51], v[128:131], v[168:171], v[48:51]
	v_mfma_f32_16x16x32_bf16 v[40:43], v[132:135], v[168:171], v[40:43]
	v_mfma_f32_16x16x32_bf16 v[32:35], v[128:131], v[172:175], v[32:35]
	v_mfma_f32_16x16x32_bf16 v[24:27], v[132:135], v[172:175], v[24:27]
	v_mfma_f32_16x16x32_bf16 v[16:19], v[128:131], v[176:179], v[16:19]
	v_mfma_f32_16x16x32_bf16 v[8:11], v[132:135], v[176:179], v[8:11]
	global_load_dwordx4 v[128:131], v108, s[8:9] offset:1344
	global_load_dwordx4 v[132:135], v109, s[8:9] offset:1344
	global_load_dwordx4 v[136:139], v92, s[38:39] offset:1344
	global_load_dwordx4 v[140:143], v93, s[38:39] offset:1344
	global_load_dwordx4 v[144:147], v94, s[38:39] offset:1344
	global_load_dwordx4 v[148:151], v95, s[38:39] offset:1344
	global_load_dwordx4 v[164:167], v100, s[38:39] offset:1344
	global_load_dwordx4 v[168:171], v101, s[38:39] offset:1344
	global_load_dwordx4 v[172:175], v102, s[38:39] offset:1344
	global_load_dwordx4 v[176:179], v103, s[38:39] offset:1344
	s_waitcnt vmcnt(20)
	v_mfma_f32_16x16x32_bf16 v[124:127], v[188:191], v[206:209], v[124:127]
	v_mfma_f32_16x16x32_bf16 v[120:123], v[202:205], v[206:209], v[120:123]
	v_mfma_f32_16x16x32_bf16 v[112:115], v[188:191], v[210:213], v[112:115]
	v_mfma_f32_16x16x32_bf16 v[104:107], v[202:205], v[210:213], v[104:107]
	v_mfma_f32_16x16x32_bf16 v[96:99], v[188:191], v[214:217], v[96:99]
	v_mfma_f32_16x16x32_bf16 v[88:91], v[202:205], v[214:217], v[88:91]
	v_mfma_f32_16x16x32_bf16 v[80:83], v[188:191], v[218:221], v[80:83]
	v_mfma_f32_16x16x32_bf16 v[72:75], v[202:205], v[218:221], v[72:75]
	v_mfma_f32_16x16x32_bf16 v[60:63], v[188:191], v[222:225], v[60:63]
	v_mfma_f32_16x16x32_bf16 v[56:59], v[202:205], v[222:225], v[56:59]
	v_mfma_f32_16x16x32_bf16 v[48:51], v[188:191], v[226:229], v[48:51]
	v_mfma_f32_16x16x32_bf16 v[40:43], v[202:205], v[226:229], v[40:43]
	v_mfma_f32_16x16x32_bf16 v[32:35], v[188:191], v[0:3], v[32:35]
	v_mfma_f32_16x16x32_bf16 v[24:27], v[202:205], v[0:3], v[24:27]
	v_mfma_f32_16x16x32_bf16 v[16:19], v[188:191], v[4:7], v[16:19]
	v_mfma_f32_16x16x32_bf16 v[8:11], v[202:205], v[4:7], v[8:11]
	global_load_dwordx4 v[188:191], v108, s[8:9] offset:1408
	global_load_dwordx4 v[202:205], v109, s[8:9] offset:1408
	global_load_dwordx4 v[206:209], v92, s[38:39] offset:1408
	global_load_dwordx4 v[210:213], v93, s[38:39] offset:1408
	global_load_dwordx4 v[214:217], v94, s[38:39] offset:1408
	global_load_dwordx4 v[218:221], v95, s[38:39] offset:1408
	global_load_dwordx4 v[222:225], v100, s[38:39] offset:1408
	global_load_dwordx4 v[226:229], v101, s[38:39] offset:1408
	global_load_dwordx4 v[0:3], v102, s[38:39] offset:1408
	global_load_dwordx4 v[4:7], v103, s[38:39] offset:1408
	s_waitcnt vmcnt(20)
	v_mfma_f32_16x16x32_bf16 v[124:127], v[12:15], v[28:31], v[124:127]
	v_mfma_f32_16x16x32_bf16 v[120:123], v[20:23], v[28:31], v[120:123]
	v_mfma_f32_16x16x32_bf16 v[112:115], v[12:15], v[36:39], v[112:115]
	v_mfma_f32_16x16x32_bf16 v[104:107], v[20:23], v[36:39], v[104:107]
	v_mfma_f32_16x16x32_bf16 v[96:99], v[12:15], v[44:47], v[96:99]
	v_mfma_f32_16x16x32_bf16 v[88:91], v[20:23], v[44:47], v[88:91]
	v_mfma_f32_16x16x32_bf16 v[80:83], v[12:15], v[52:55], v[80:83]
	v_mfma_f32_16x16x32_bf16 v[72:75], v[20:23], v[52:55], v[72:75]
	v_mfma_f32_16x16x32_bf16 v[60:63], v[12:15], v[64:67], v[60:63]
	v_mfma_f32_16x16x32_bf16 v[56:59], v[20:23], v[64:67], v[56:59]
	v_mfma_f32_16x16x32_bf16 v[48:51], v[12:15], v[68:71], v[48:51]
	v_mfma_f32_16x16x32_bf16 v[40:43], v[20:23], v[68:71], v[40:43]
	v_mfma_f32_16x16x32_bf16 v[32:35], v[12:15], v[76:79], v[32:35]
	v_mfma_f32_16x16x32_bf16 v[24:27], v[20:23], v[76:79], v[24:27]
	v_mfma_f32_16x16x32_bf16 v[16:19], v[12:15], v[84:87], v[16:19]
	v_mfma_f32_16x16x32_bf16 v[8:11], v[20:23], v[84:87], v[8:11]
	global_load_dwordx4 v[12:15], v108, s[8:9] offset:1472
	global_load_dwordx4 v[20:23], v109, s[8:9] offset:1472
	global_load_dwordx4 v[28:31], v92, s[38:39] offset:1472
	global_load_dwordx4 v[36:39], v93, s[38:39] offset:1472
	global_load_dwordx4 v[44:47], v94, s[38:39] offset:1472
	global_load_dwordx4 v[52:55], v95, s[38:39] offset:1472
	global_load_dwordx4 v[64:67], v100, s[38:39] offset:1472
	global_load_dwordx4 v[68:71], v101, s[38:39] offset:1472
	global_load_dwordx4 v[76:79], v102, s[38:39] offset:1472
	global_load_dwordx4 v[84:87], v103, s[38:39] offset:1472
	s_waitcnt vmcnt(20)
	v_mfma_f32_16x16x32_bf16 v[124:127], v[128:131], v[136:139], v[124:127]
	v_mfma_f32_16x16x32_bf16 v[120:123], v[132:135], v[136:139], v[120:123]
	v_mfma_f32_16x16x32_bf16 v[112:115], v[128:131], v[140:143], v[112:115]
	v_mfma_f32_16x16x32_bf16 v[104:107], v[132:135], v[140:143], v[104:107]
	v_mfma_f32_16x16x32_bf16 v[96:99], v[128:131], v[144:147], v[96:99]
	v_mfma_f32_16x16x32_bf16 v[88:91], v[132:135], v[144:147], v[88:91]
	v_mfma_f32_16x16x32_bf16 v[80:83], v[128:131], v[148:151], v[80:83]
	v_mfma_f32_16x16x32_bf16 v[72:75], v[132:135], v[148:151], v[72:75]
	v_mfma_f32_16x16x32_bf16 v[60:63], v[128:131], v[164:167], v[60:63]
	v_mfma_f32_16x16x32_bf16 v[56:59], v[132:135], v[164:167], v[56:59]
	v_mfma_f32_16x16x32_bf16 v[48:51], v[128:131], v[168:171], v[48:51]
	v_mfma_f32_16x16x32_bf16 v[40:43], v[132:135], v[168:171], v[40:43]
	v_mfma_f32_16x16x32_bf16 v[32:35], v[128:131], v[172:175], v[32:35]
	v_mfma_f32_16x16x32_bf16 v[24:27], v[132:135], v[172:175], v[24:27]
	v_mfma_f32_16x16x32_bf16 v[16:19], v[128:131], v[176:179], v[16:19]
	v_mfma_f32_16x16x32_bf16 v[8:11], v[132:135], v[176:179], v[8:11]
	global_load_dwordx4 v[128:131], v108, s[8:9] offset:1536
	global_load_dwordx4 v[132:135], v109, s[8:9] offset:1536
	global_load_dwordx4 v[136:139], v92, s[38:39] offset:1536
	global_load_dwordx4 v[140:143], v93, s[38:39] offset:1536
	global_load_dwordx4 v[144:147], v94, s[38:39] offset:1536
	global_load_dwordx4 v[148:151], v95, s[38:39] offset:1536
	global_load_dwordx4 v[164:167], v100, s[38:39] offset:1536
	global_load_dwordx4 v[168:171], v101, s[38:39] offset:1536
	global_load_dwordx4 v[172:175], v102, s[38:39] offset:1536
	global_load_dwordx4 v[176:179], v103, s[38:39] offset:1536
	s_waitcnt vmcnt(20)
	v_mfma_f32_16x16x32_bf16 v[124:127], v[188:191], v[206:209], v[124:127]
	v_mfma_f32_16x16x32_bf16 v[120:123], v[202:205], v[206:209], v[120:123]
	v_mfma_f32_16x16x32_bf16 v[112:115], v[188:191], v[210:213], v[112:115]
	v_mfma_f32_16x16x32_bf16 v[104:107], v[202:205], v[210:213], v[104:107]
	v_mfma_f32_16x16x32_bf16 v[96:99], v[188:191], v[214:217], v[96:99]
	v_mfma_f32_16x16x32_bf16 v[88:91], v[202:205], v[214:217], v[88:91]
	v_mfma_f32_16x16x32_bf16 v[80:83], v[188:191], v[218:221], v[80:83]
	v_mfma_f32_16x16x32_bf16 v[72:75], v[202:205], v[218:221], v[72:75]
	v_mfma_f32_16x16x32_bf16 v[60:63], v[188:191], v[222:225], v[60:63]
	v_mfma_f32_16x16x32_bf16 v[56:59], v[202:205], v[222:225], v[56:59]
	v_mfma_f32_16x16x32_bf16 v[48:51], v[188:191], v[226:229], v[48:51]
	v_mfma_f32_16x16x32_bf16 v[40:43], v[202:205], v[226:229], v[40:43]
	v_mfma_f32_16x16x32_bf16 v[32:35], v[188:191], v[0:3], v[32:35]
	v_mfma_f32_16x16x32_bf16 v[24:27], v[202:205], v[0:3], v[24:27]
	v_mfma_f32_16x16x32_bf16 v[16:19], v[188:191], v[4:7], v[16:19]
	v_mfma_f32_16x16x32_bf16 v[8:11], v[202:205], v[4:7], v[8:11]
	global_load_dwordx4 v[188:191], v108, s[8:9] offset:1600
	global_load_dwordx4 v[202:205], v109, s[8:9] offset:1600
	global_load_dwordx4 v[206:209], v92, s[38:39] offset:1600
	global_load_dwordx4 v[210:213], v93, s[38:39] offset:1600
	global_load_dwordx4 v[214:217], v94, s[38:39] offset:1600
	global_load_dwordx4 v[218:221], v95, s[38:39] offset:1600
	global_load_dwordx4 v[222:225], v100, s[38:39] offset:1600
	global_load_dwordx4 v[226:229], v101, s[38:39] offset:1600
	global_load_dwordx4 v[0:3], v102, s[38:39] offset:1600
	global_load_dwordx4 v[4:7], v103, s[38:39] offset:1600
	s_waitcnt vmcnt(20)
	v_mfma_f32_16x16x32_bf16 v[124:127], v[12:15], v[28:31], v[124:127]
	v_mfma_f32_16x16x32_bf16 v[120:123], v[20:23], v[28:31], v[120:123]
	v_mfma_f32_16x16x32_bf16 v[112:115], v[12:15], v[36:39], v[112:115]
	v_mfma_f32_16x16x32_bf16 v[104:107], v[20:23], v[36:39], v[104:107]
	v_mfma_f32_16x16x32_bf16 v[96:99], v[12:15], v[44:47], v[96:99]
	v_mfma_f32_16x16x32_bf16 v[88:91], v[20:23], v[44:47], v[88:91]
	v_mfma_f32_16x16x32_bf16 v[80:83], v[12:15], v[52:55], v[80:83]
	v_mfma_f32_16x16x32_bf16 v[72:75], v[20:23], v[52:55], v[72:75]
	v_mfma_f32_16x16x32_bf16 v[60:63], v[12:15], v[64:67], v[60:63]
	v_mfma_f32_16x16x32_bf16 v[56:59], v[20:23], v[64:67], v[56:59]
	v_mfma_f32_16x16x32_bf16 v[48:51], v[12:15], v[68:71], v[48:51]
	v_mfma_f32_16x16x32_bf16 v[40:43], v[20:23], v[68:71], v[40:43]
	v_mfma_f32_16x16x32_bf16 v[32:35], v[12:15], v[76:79], v[32:35]
	v_mfma_f32_16x16x32_bf16 v[24:27], v[20:23], v[76:79], v[24:27]
	v_mfma_f32_16x16x32_bf16 v[16:19], v[12:15], v[84:87], v[16:19]
	v_mfma_f32_16x16x32_bf16 v[8:11], v[20:23], v[84:87], v[8:11]
	global_load_dwordx4 v[12:15], v108, s[8:9] offset:1664
	global_load_dwordx4 v[20:23], v109, s[8:9] offset:1664
	global_load_dwordx4 v[28:31], v92, s[38:39] offset:1664
	global_load_dwordx4 v[36:39], v93, s[38:39] offset:1664
	global_load_dwordx4 v[44:47], v94, s[38:39] offset:1664
	global_load_dwordx4 v[52:55], v95, s[38:39] offset:1664
	global_load_dwordx4 v[64:67], v100, s[38:39] offset:1664
	global_load_dwordx4 v[68:71], v101, s[38:39] offset:1664
	global_load_dwordx4 v[76:79], v102, s[38:39] offset:1664
	global_load_dwordx4 v[84:87], v103, s[38:39] offset:1664
	s_waitcnt vmcnt(20)
	v_mfma_f32_16x16x32_bf16 v[124:127], v[128:131], v[136:139], v[124:127]
	v_mfma_f32_16x16x32_bf16 v[120:123], v[132:135], v[136:139], v[120:123]
	v_mfma_f32_16x16x32_bf16 v[112:115], v[128:131], v[140:143], v[112:115]
	v_mfma_f32_16x16x32_bf16 v[104:107], v[132:135], v[140:143], v[104:107]
	v_mfma_f32_16x16x32_bf16 v[96:99], v[128:131], v[144:147], v[96:99]
	v_mfma_f32_16x16x32_bf16 v[88:91], v[132:135], v[144:147], v[88:91]
	v_mfma_f32_16x16x32_bf16 v[80:83], v[128:131], v[148:151], v[80:83]
	v_mfma_f32_16x16x32_bf16 v[72:75], v[132:135], v[148:151], v[72:75]
	v_mfma_f32_16x16x32_bf16 v[60:63], v[128:131], v[164:167], v[60:63]
	v_mfma_f32_16x16x32_bf16 v[56:59], v[132:135], v[164:167], v[56:59]
	v_mfma_f32_16x16x32_bf16 v[48:51], v[128:131], v[168:171], v[48:51]
	v_mfma_f32_16x16x32_bf16 v[40:43], v[132:135], v[168:171], v[40:43]
	v_mfma_f32_16x16x32_bf16 v[32:35], v[128:131], v[172:175], v[32:35]
	v_mfma_f32_16x16x32_bf16 v[24:27], v[132:135], v[172:175], v[24:27]
	v_mfma_f32_16x16x32_bf16 v[16:19], v[128:131], v[176:179], v[16:19]
	v_mfma_f32_16x16x32_bf16 v[8:11], v[132:135], v[176:179], v[8:11]
	global_load_dwordx4 v[128:131], v108, s[8:9] offset:1728
	global_load_dwordx4 v[132:135], v109, s[8:9] offset:1728
	global_load_dwordx4 v[136:139], v92, s[38:39] offset:1728
	global_load_dwordx4 v[140:143], v93, s[38:39] offset:1728
	global_load_dwordx4 v[144:147], v94, s[38:39] offset:1728
	global_load_dwordx4 v[148:151], v95, s[38:39] offset:1728
	global_load_dwordx4 v[164:167], v100, s[38:39] offset:1728
	global_load_dwordx4 v[168:171], v101, s[38:39] offset:1728
	global_load_dwordx4 v[172:175], v102, s[38:39] offset:1728
	global_load_dwordx4 v[176:179], v103, s[38:39] offset:1728
	s_waitcnt vmcnt(20)
	v_mfma_f32_16x16x32_bf16 v[124:127], v[188:191], v[206:209], v[124:127]
	v_mfma_f32_16x16x32_bf16 v[120:123], v[202:205], v[206:209], v[120:123]
	v_mfma_f32_16x16x32_bf16 v[112:115], v[188:191], v[210:213], v[112:115]
	v_mfma_f32_16x16x32_bf16 v[104:107], v[202:205], v[210:213], v[104:107]
	v_mfma_f32_16x16x32_bf16 v[96:99], v[188:191], v[214:217], v[96:99]
	v_mfma_f32_16x16x32_bf16 v[88:91], v[202:205], v[214:217], v[88:91]
	v_mfma_f32_16x16x32_bf16 v[80:83], v[188:191], v[218:221], v[80:83]
	v_mfma_f32_16x16x32_bf16 v[72:75], v[202:205], v[218:221], v[72:75]
	v_mfma_f32_16x16x32_bf16 v[60:63], v[188:191], v[222:225], v[60:63]
	v_mfma_f32_16x16x32_bf16 v[56:59], v[202:205], v[222:225], v[56:59]
	v_mfma_f32_16x16x32_bf16 v[48:51], v[188:191], v[226:229], v[48:51]
	v_mfma_f32_16x16x32_bf16 v[40:43], v[202:205], v[226:229], v[40:43]
	v_mfma_f32_16x16x32_bf16 v[32:35], v[188:191], v[0:3], v[32:35]
	v_mfma_f32_16x16x32_bf16 v[24:27], v[202:205], v[0:3], v[24:27]
	v_mfma_f32_16x16x32_bf16 v[16:19], v[188:191], v[4:7], v[16:19]
	v_mfma_f32_16x16x32_bf16 v[8:11], v[202:205], v[4:7], v[8:11]
	global_load_dwordx4 v[188:191], v108, s[8:9] offset:1792
	global_load_dwordx4 v[202:205], v109, s[8:9] offset:1792
	global_load_dwordx4 v[206:209], v92, s[38:39] offset:1792
	global_load_dwordx4 v[210:213], v93, s[38:39] offset:1792
	global_load_dwordx4 v[214:217], v94, s[38:39] offset:1792
	global_load_dwordx4 v[218:221], v95, s[38:39] offset:1792
	global_load_dwordx4 v[222:225], v100, s[38:39] offset:1792
	global_load_dwordx4 v[226:229], v101, s[38:39] offset:1792
	global_load_dwordx4 v[0:3], v102, s[38:39] offset:1792
	global_load_dwordx4 v[4:7], v103, s[38:39] offset:1792
	s_waitcnt vmcnt(20)
	v_mfma_f32_16x16x32_bf16 v[124:127], v[12:15], v[28:31], v[124:127]
	v_mfma_f32_16x16x32_bf16 v[120:123], v[20:23], v[28:31], v[120:123]
	v_mfma_f32_16x16x32_bf16 v[112:115], v[12:15], v[36:39], v[112:115]
	v_mfma_f32_16x16x32_bf16 v[104:107], v[20:23], v[36:39], v[104:107]
	v_mfma_f32_16x16x32_bf16 v[96:99], v[12:15], v[44:47], v[96:99]
	v_mfma_f32_16x16x32_bf16 v[88:91], v[20:23], v[44:47], v[88:91]
	v_mfma_f32_16x16x32_bf16 v[80:83], v[12:15], v[52:55], v[80:83]
	v_mfma_f32_16x16x32_bf16 v[72:75], v[20:23], v[52:55], v[72:75]
	v_mfma_f32_16x16x32_bf16 v[60:63], v[12:15], v[64:67], v[60:63]
	v_mfma_f32_16x16x32_bf16 v[56:59], v[20:23], v[64:67], v[56:59]
	v_mfma_f32_16x16x32_bf16 v[48:51], v[12:15], v[68:71], v[48:51]
	v_mfma_f32_16x16x32_bf16 v[40:43], v[20:23], v[68:71], v[40:43]
	v_mfma_f32_16x16x32_bf16 v[32:35], v[12:15], v[76:79], v[32:35]
	v_mfma_f32_16x16x32_bf16 v[24:27], v[20:23], v[76:79], v[24:27]
	v_mfma_f32_16x16x32_bf16 v[16:19], v[12:15], v[84:87], v[16:19]
	v_mfma_f32_16x16x32_bf16 v[8:11], v[20:23], v[84:87], v[8:11]
	global_load_dwordx4 v[12:15], v108, s[8:9] offset:1856
	global_load_dwordx4 v[20:23], v109, s[8:9] offset:1856
	global_load_dwordx4 v[28:31], v92, s[38:39] offset:1856
	global_load_dwordx4 v[36:39], v93, s[38:39] offset:1856
	global_load_dwordx4 v[44:47], v94, s[38:39] offset:1856
	global_load_dwordx4 v[52:55], v95, s[38:39] offset:1856
	global_load_dwordx4 v[64:67], v100, s[38:39] offset:1856
	global_load_dwordx4 v[68:71], v101, s[38:39] offset:1856
	global_load_dwordx4 v[76:79], v102, s[38:39] offset:1856
	global_load_dwordx4 v[84:87], v103, s[38:39] offset:1856
	s_waitcnt vmcnt(20)
	v_mfma_f32_16x16x32_bf16 v[124:127], v[128:131], v[136:139], v[124:127]
	v_mfma_f32_16x16x32_bf16 v[120:123], v[132:135], v[136:139], v[120:123]
	v_mfma_f32_16x16x32_bf16 v[112:115], v[128:131], v[140:143], v[112:115]
	v_mfma_f32_16x16x32_bf16 v[104:107], v[132:135], v[140:143], v[104:107]
	v_mfma_f32_16x16x32_bf16 v[96:99], v[128:131], v[144:147], v[96:99]
	v_mfma_f32_16x16x32_bf16 v[88:91], v[132:135], v[144:147], v[88:91]
	v_mfma_f32_16x16x32_bf16 v[80:83], v[128:131], v[148:151], v[80:83]
	v_mfma_f32_16x16x32_bf16 v[72:75], v[132:135], v[148:151], v[72:75]
	v_mfma_f32_16x16x32_bf16 v[60:63], v[128:131], v[164:167], v[60:63]
	v_mfma_f32_16x16x32_bf16 v[56:59], v[132:135], v[164:167], v[56:59]
	v_mfma_f32_16x16x32_bf16 v[48:51], v[128:131], v[168:171], v[48:51]
	v_mfma_f32_16x16x32_bf16 v[40:43], v[132:135], v[168:171], v[40:43]
	v_mfma_f32_16x16x32_bf16 v[32:35], v[128:131], v[172:175], v[32:35]
	v_mfma_f32_16x16x32_bf16 v[24:27], v[132:135], v[172:175], v[24:27]
	v_mfma_f32_16x16x32_bf16 v[16:19], v[128:131], v[176:179], v[16:19]
	v_mfma_f32_16x16x32_bf16 v[8:11], v[132:135], v[176:179], v[8:11]
	global_load_dwordx4 v[128:131], v108, s[8:9] offset:1920
	global_load_dwordx4 v[132:135], v109, s[8:9] offset:1920
	global_load_dwordx4 v[136:139], v92, s[38:39] offset:1920
	global_load_dwordx4 v[140:143], v93, s[38:39] offset:1920
	global_load_dwordx4 v[144:147], v94, s[38:39] offset:1920
	global_load_dwordx4 v[148:151], v95, s[38:39] offset:1920
	global_load_dwordx4 v[164:167], v100, s[38:39] offset:1920
	global_load_dwordx4 v[168:171], v101, s[38:39] offset:1920
	global_load_dwordx4 v[172:175], v102, s[38:39] offset:1920
	global_load_dwordx4 v[176:179], v103, s[38:39] offset:1920
	s_waitcnt vmcnt(20)
	v_mfma_f32_16x16x32_bf16 v[124:127], v[188:191], v[206:209], v[124:127]
	v_mfma_f32_16x16x32_bf16 v[120:123], v[202:205], v[206:209], v[120:123]
	v_mfma_f32_16x16x32_bf16 v[112:115], v[188:191], v[210:213], v[112:115]
	v_mfma_f32_16x16x32_bf16 v[104:107], v[202:205], v[210:213], v[104:107]
	v_mfma_f32_16x16x32_bf16 v[96:99], v[188:191], v[214:217], v[96:99]
	v_mfma_f32_16x16x32_bf16 v[88:91], v[202:205], v[214:217], v[88:91]
	v_mfma_f32_16x16x32_bf16 v[80:83], v[188:191], v[218:221], v[80:83]
	v_mfma_f32_16x16x32_bf16 v[72:75], v[202:205], v[218:221], v[72:75]
	v_mfma_f32_16x16x32_bf16 v[60:63], v[188:191], v[222:225], v[60:63]
	v_mfma_f32_16x16x32_bf16 v[56:59], v[202:205], v[222:225], v[56:59]
	v_mfma_f32_16x16x32_bf16 v[48:51], v[188:191], v[226:229], v[48:51]
	v_mfma_f32_16x16x32_bf16 v[40:43], v[202:205], v[226:229], v[40:43]
	v_mfma_f32_16x16x32_bf16 v[32:35], v[188:191], v[0:3], v[32:35]
	v_mfma_f32_16x16x32_bf16 v[24:27], v[202:205], v[0:3], v[24:27]
	v_mfma_f32_16x16x32_bf16 v[16:19], v[188:191], v[4:7], v[16:19]
	v_mfma_f32_16x16x32_bf16 v[8:11], v[202:205], v[4:7], v[8:11]
	global_load_dwordx4 v[188:191], v108, s[8:9] offset:1984
	global_load_dwordx4 v[202:205], v109, s[8:9] offset:1984
	global_load_dwordx4 v[206:209], v92, s[38:39] offset:1984
	global_load_dwordx4 v[210:213], v93, s[38:39] offset:1984
	global_load_dwordx4 v[214:217], v94, s[38:39] offset:1984
	global_load_dwordx4 v[218:221], v95, s[38:39] offset:1984
	global_load_dwordx4 v[222:225], v100, s[38:39] offset:1984
	global_load_dwordx4 v[226:229], v101, s[38:39] offset:1984
	global_load_dwordx4 v[0:3], v102, s[38:39] offset:1984
	global_load_dwordx4 v[4:7], v103, s[38:39] offset:1984
	s_waitcnt vmcnt(20)
	v_mfma_f32_16x16x32_bf16 v[124:127], v[12:15], v[28:31], v[124:127]
	v_mfma_f32_16x16x32_bf16 v[120:123], v[20:23], v[28:31], v[120:123]
	v_mfma_f32_16x16x32_bf16 v[112:115], v[12:15], v[36:39], v[112:115]
	v_mfma_f32_16x16x32_bf16 v[104:107], v[20:23], v[36:39], v[104:107]
	v_mfma_f32_16x16x32_bf16 v[96:99], v[12:15], v[44:47], v[96:99]
	v_mfma_f32_16x16x32_bf16 v[88:91], v[20:23], v[44:47], v[88:91]
	v_mfma_f32_16x16x32_bf16 v[80:83], v[12:15], v[52:55], v[80:83]
	v_mfma_f32_16x16x32_bf16 v[72:75], v[20:23], v[52:55], v[72:75]
	v_mfma_f32_16x16x32_bf16 v[60:63], v[12:15], v[64:67], v[60:63]
	v_mfma_f32_16x16x32_bf16 v[56:59], v[20:23], v[64:67], v[56:59]
	v_mfma_f32_16x16x32_bf16 v[48:51], v[12:15], v[68:71], v[48:51]
	v_mfma_f32_16x16x32_bf16 v[40:43], v[20:23], v[68:71], v[40:43]
	v_mfma_f32_16x16x32_bf16 v[32:35], v[12:15], v[76:79], v[32:35]
	v_mfma_f32_16x16x32_bf16 v[24:27], v[20:23], v[76:79], v[24:27]
	v_mfma_f32_16x16x32_bf16 v[16:19], v[12:15], v[84:87], v[16:19]
	v_mfma_f32_16x16x32_bf16 v[8:11], v[20:23], v[84:87], v[8:11]
	s_waitcnt vmcnt(10)
	v_mfma_f32_16x16x32_bf16 v[124:127], v[128:131], v[136:139], v[124:127]
	v_mfma_f32_16x16x32_bf16 v[120:123], v[132:135], v[136:139], v[120:123]
	v_mfma_f32_16x16x32_bf16 v[112:115], v[128:131], v[140:143], v[112:115]
	v_mfma_f32_16x16x32_bf16 v[104:107], v[132:135], v[140:143], v[104:107]
	v_mfma_f32_16x16x32_bf16 v[96:99], v[128:131], v[144:147], v[96:99]
	v_mfma_f32_16x16x32_bf16 v[88:91], v[132:135], v[144:147], v[88:91]
	v_mfma_f32_16x16x32_bf16 v[80:83], v[128:131], v[148:151], v[80:83]
	v_mfma_f32_16x16x32_bf16 v[72:75], v[132:135], v[148:151], v[72:75]
	v_mfma_f32_16x16x32_bf16 v[60:63], v[128:131], v[164:167], v[60:63]
	v_mfma_f32_16x16x32_bf16 v[56:59], v[132:135], v[164:167], v[56:59]
	v_mfma_f32_16x16x32_bf16 v[48:51], v[128:131], v[168:171], v[48:51]
	v_mfma_f32_16x16x32_bf16 v[40:43], v[132:135], v[168:171], v[40:43]
	v_mfma_f32_16x16x32_bf16 v[32:35], v[128:131], v[172:175], v[32:35]
	v_mfma_f32_16x16x32_bf16 v[24:27], v[132:135], v[172:175], v[24:27]
	v_mfma_f32_16x16x32_bf16 v[16:19], v[128:131], v[176:179], v[16:19]
	v_mfma_f32_16x16x32_bf16 v[8:11], v[132:135], v[176:179], v[8:11]
	s_waitcnt vmcnt(0)
	v_mfma_f32_16x16x32_bf16 v[124:127], v[188:191], v[206:209], v[124:127]
	v_mfma_f32_16x16x32_bf16 v[120:123], v[202:205], v[206:209], v[120:123]
	v_mfma_f32_16x16x32_bf16 v[112:115], v[188:191], v[210:213], v[112:115]
	v_mfma_f32_16x16x32_bf16 v[104:107], v[202:205], v[210:213], v[104:107]
	v_mfma_f32_16x16x32_bf16 v[96:99], v[188:191], v[214:217], v[96:99]
	v_mfma_f32_16x16x32_bf16 v[88:91], v[202:205], v[214:217], v[88:91]
	v_mfma_f32_16x16x32_bf16 v[80:83], v[188:191], v[218:221], v[80:83]
	v_mfma_f32_16x16x32_bf16 v[72:75], v[202:205], v[218:221], v[72:75]
	v_mfma_f32_16x16x32_bf16 v[60:63], v[188:191], v[222:225], v[60:63]
	v_mfma_f32_16x16x32_bf16 v[56:59], v[202:205], v[222:225], v[56:59]
	v_mfma_f32_16x16x32_bf16 v[48:51], v[188:191], v[226:229], v[48:51]
	v_mfma_f32_16x16x32_bf16 v[40:43], v[202:205], v[226:229], v[40:43]
	v_mfma_f32_16x16x32_bf16 v[32:35], v[188:191], v[0:3], v[32:35]
	v_mfma_f32_16x16x32_bf16 v[24:27], v[202:205], v[0:3], v[24:27]
	v_mfma_f32_16x16x32_bf16 v[16:19], v[188:191], v[4:7], v[16:19]
	v_mfma_f32_16x16x32_bf16 v[8:11], v[202:205], v[4:7], v[8:11]
.Lzc_skip:
	s_waitcnt vmcnt(0)
	s_barrier
	s_barrier
	s_add_u32 s88, s8, 0x100
	s_addc_u32 s89, s9, 0
	s_add_u32 s8, s38, 0x40080
	s_addc_u32 s9, s39, 0
	s_mov_b32 s90, -2
	s_add_u32 s38, s8, 0xfffc0080
	s_addc_u32 s39, s9, -1
	s_add_i32 s91, 0, 0x10000
	s_cmp_eq_u32 s90, 12
	s_cselect_b32 s57, s31, s39
	s_cselect_b32 s56, s47, s38
	s_cselect_b32 s39, s29, s89
	s_cselect_b32 s38, s87, s88
	s_add_i32 s94, 0, 0x14000
	s_add_i32 s85, s85, 1
	s_mul_i32 s6, s85, s43
	s_mul_hi_u32 s7, s85, s42
	s_add_i32 s7, s7, s6
	s_mul_i32 s6, s85, s42
	s_add_u32 s34, s6, s2
	s_addc_u32 s35, s7, s41
	v_mov_b64_e32 v[0:1], 0xf00
	v_cmp_lt_i64_e64 s[6:7], s[34:35], v[0:1]
	v_mov_b64_e32 v[0:1], 0xeff
	v_cmp_gt_i64_e32 vcc, s[34:35], v[0:1]
	s_cbranch_vccnz .Lz257
	s_ashr_i32 s28, s34, 31
	s_lshr_b32 s28, s28, 29
	s_add_i32 s28, s34, s28
	s_ashr_i32 s29, s28, 3
	s_and_b32 s28, s28, -8
	s_sub_i32 s28, s34, s28
	s_cmp_lt_i32 s28, 0
	s_movk_i32 s30, 0x1e1
	s_cselect_b32 s30, s30, 0x1e0
	s_mul_i32 s28, s28, s30
	s_add_i32 s28, s28, s29
	s_mul_hi_i32 s29, s28, 0x88888889
	s_add_i32 s29, s29, s28
	s_lshr_b32 s30, s29, 31
	s_ashr_i32 s29, s29, 6
	s_add_i32 s29, s29, s30
	s_lshl_b32 s30, s29, 3
	s_sub_i32 s31, 0x100, s30
	s_min_i32 s31, s31, 8
	s_abs_i32 s34, s31
	v_cvt_f32_u32_e32 v0, s34
	s_sub_i32 s36, 0, s34
	s_mulk_i32 s29, 0x78
	s_sub_i32 s29, s28, s29
	v_rcp_iflag_f32_e32 v0, v0
	s_abs_i32 s28, s29
	s_xor_b32 s35, s29, s31
	s_ashr_i32 s35, s35, 31
	v_mul_f32_e32 v0, 0x4f7ffffe, v0
	v_cvt_u32_f32_e32 v0, v0
	s_nop 0
	v_readfirstlane_b32 s37, v0
	s_mul_i32 s36, s36, s37
	s_mul_hi_u32 s36, s37, s36
	s_add_i32 s37, s37, s36
	s_mul_hi_u32 s36, s28, s37
	s_mul_i32 s37, s36, s34
	s_sub_i32 s28, s28, s37
	s_add_i32 s47, s36, 1
	s_sub_i32 s37, s28, s34
	s_cmp_ge_u32 s28, s34
	s_cselect_b32 s36, s47, s36
	s_cselect_b32 s28, s37, s28
	s_add_i32 s37, s36, 1
	s_cmp_ge_u32 s28, s34
	s_cselect_b32 s28, s37, s36
	s_xor_b32 s28, s28, s35
	s_sub_i32 s28, s28, s35
	s_mul_i32 s31, s28, s31
	s_sub_i32 s29, s29, s31
	s_add_i32 s30, s30, s29
.Lz257:
	s_ashr_i32 s31, s30, 31
	s_lshl_b64 s[34:35], s[30:31], 19
	s_add_u32 s34, s48, s34
	s_addc_u32 s35, s49, s35
	s_and_b64 s[36:37], s[6:7], exec
	s_cselect_b32 s31, s35, s57
	s_cselect_b32 s47, s34, s56
	s_ashr_i32 s29, s28, 31
	s_lshl_b64 s[36:37], s[28:29], 19
	s_add_u32 s36, s50, s36
	s_addc_u32 s37, s51, s37
	s_and_b64 s[100:101], s[6:7], exec
	s_cselect_b32 s29, s37, s89
	s_cselect_b32 s87, s36, s88
	s_mov_b32 s90, 12
	s_add_u32 s38, s8, 0xfffc0080
	s_addc_u32 s39, s9, -1
	s_add_i32 s91, 0, 0x10000
	s_cmp_eq_u32 s90, 12
	s_cselect_b32 s57, s31, s39
	s_cselect_b32 s56, s47, s38
	s_cselect_b32 s39, s29, s89
	s_cselect_b32 s38, s87, s88
	s_add_i32 s94, 0, 0x14000
	v_add_u32_e32 v140, s91, v183
	v_add_u32_e32 v168, s94, v183
	v_lshl_add_u64 v[184:185], s[8:9], 0, v[162:163]
	s_add_i32 m0, s55, 0xc000
	global_load_lds_dwordx4 v[184:185], off
	v_lshl_add_u64 v[184:185], s[8:9], 0, v[160:161]
	s_add_i32 m0, s55, 0xe000
	s_nop 0
	global_load_lds_dwordx4 v[184:185], off
	s_waitcnt vmcnt(8)
	s_waitcnt lgkmcnt(0)
	s_barrier
	s_setprio 1
	s_waitcnt lgkmcnt(0)
	s_setprio 0
	s_setprio 1
	s_setprio 0
	s_barrier
	s_add_i32 s91, s91, s54
	v_lshl_add_u64 v[184:185], s[38:39], 0, v[192:193]
	s_mov_b32 m0, s91
	global_load_lds_dwordx4 v[184:185], off
	s_add_i32 m0, s91, 0x2000
	s_add_u32 s92, s38, 0x40000
	v_lshl_add_u64 v[222:223], s[38:39], 0, v[152:153]
	s_addc_u32 s93, s39, 0
	s_add_i32 s91, s94, s54
	global_load_lds_dwordx4 v[222:223], off
	v_lshl_add_u64 v[224:225], s[92:93], 0, v[192:193]
	s_mov_b32 m0, s91
	v_lshl_add_u64 v[226:227], s[56:57], 0, v[154:155]
	global_load_lds_dwordx4 v[224:225], off
	v_lshl_add_u64 v[224:225], s[92:93], 0, v[152:153]
	s_add_i32 m0, s91, 0x2000
	s_nop 0
	global_load_lds_dwordx4 v[224:225], off
	v_lshl_add_u64 v[224:225], s[56:57], 0, v[156:157]
	s_mov_b32 m0, s55
	s_nop 0
	global_load_lds_dwordx4 v[224:225], off
	s_mov_b32 m0, s60
	s_nop 0
	global_load_lds_dwordx4 v[226:227], off
	s_waitcnt vmcnt(8)
	s_waitcnt lgkmcnt(0)
	s_barrier
	s_setprio 1
	s_waitcnt lgkmcnt(0)
	s_setprio 0
	s_setprio 1
	s_setprio 0
	s_barrier
	s_add_i32 s91, 0, 0x18000
	s_add_i32 s92, 0, 0x1c000
	v_add_u32_e32 v140, s91, v183
	v_add_u32_e32 v168, s92, v183
	s_add_u32 s56, s56, 0x40000
	s_addc_u32 s57, s57, 0
	s_mov_b32 m0, s61
	v_lshl_add_u64 v[228:229], s[56:57], 0, v[156:157]
	global_load_lds_dwordx4 v[228:229], off
	v_lshl_add_u64 v[228:229], s[56:57], 0, v[154:155]
	s_mov_b32 m0, s82
	s_nop 0
	global_load_lds_dwordx4 v[228:229], off
	s_waitcnt vmcnt(8)
	s_waitcnt lgkmcnt(0)
	s_barrier
	s_setprio 1
	s_waitcnt lgkmcnt(0)
	s_setprio 0
	s_setprio 1
	s_setprio 0
	s_barrier
	s_add_i32 s56, s91, s54
	v_lshl_add_u64 v[184:185], v[184:185], 0, s[76:77]
	s_mov_b32 m0, s56
	global_load_lds_dwordx4 v[184:185], off
	s_add_i32 m0, s56, 0x2000
	s_add_u32 s38, s38, 0x40080
	v_lshl_add_u64 v[184:185], v[222:223], 0, s[76:77]
	s_addc_u32 s39, s39, 0
	s_add_i32 s56, s92, s54
	global_load_lds_dwordx4 v[184:185], off
	v_lshl_add_u64 v[184:185], s[38:39], 0, v[192:193]
	s_mov_b32 m0, s56
	s_nop 0
	global_load_lds_dwordx4 v[184:185], off
	v_lshl_add_u64 v[184:185], s[38:39], 0, v[152:153]
	s_add_i32 m0, s56, 0x2000
	s_nop 0
	global_load_lds_dwordx4 v[184:185], off
	v_lshl_add_u64 v[184:185], v[224:225], 0, s[76:77]
	s_mov_b32 m0, s68
	s_nop 0
	global_load_lds_dwordx4 v[184:185], off
	v_lshl_add_u64 v[184:185], v[226:227], 0, s[76:77]
	s_mov_b32 m0, s83
	s_nop 0
	global_load_lds_dwordx4 v[184:185], off
	s_waitcnt vmcnt(8)
	s_waitcnt lgkmcnt(0)
	s_barrier
	s_setprio 1
	s_waitcnt lgkmcnt(0)
	s_setprio 0
	s_setprio 1
	s_setprio 0
	s_barrier
	s_add_i32 s90, s90, 2
	s_add_u32 s88, s88, 0x100
	s_addc_u32 s89, s89, 0
	s_add_u32 s8, s8, 0x100
	s_addc_u32 s9, s9, 0
	s_cmp_gt_u32 s90, 13
	s_branch .LBB0_261
